# weight transposes in P0, P1 and P3: both gather iterations' loads issued before the first wait
# speedup vs baseline: 1.0046x; 1.0042x over previous
; #define LAS __attribute__((address_space(3)))
; template <bool MAP> __device__ __forceinline__ void p0_transpose_item(const float* W, int K, int NS, bf16* WT, LAS float* scr, int item, int nkb, int lane) {
;     const int pb = item / nkb, kb = item % nkb, k0 = 64 * kb, p0 = 32 * pb;
;     const int sc = MAP ? pg8::proj_src_col(p0 + (lane & 31)) : p0 + (lane & 31);
; #pragma unroll 8
;     for (int i = 0; i < 32; ++i) { const int kk = 2 * i + (lane >> 5); scr[kk * 33 + (lane & 31)] = W[(size_t)(k0 + kk) * NS + sc]; }
.LBB0_57:
	s_lshl_b32 s20, s6, 1
	s_lshl_b32 s21, s7, 1
	v_or_b32_e32 v5, s20, v1
	v_or_b32_e32 v7, s21, v4
	s_add_i32 s22, s20, 4
	s_add_i32 s23, s21, 4
	s_add_i32 s26, s20, 8
	s_add_i32 s27, s21, 8
	s_add_i32 s28, s20, 12
	s_add_i32 s29, s21, 12
	s_add_i32 s30, s20, 16
	s_add_i32 s31, s21, 16
	s_add_i32 s33, s20, 20
	s_add_i32 s34, s21, 20
	s_add_i32 s35, s20, 24
	s_add_i32 s36, s21, 24
	s_add_i32 s20, s20, 28
	s_add_i32 s21, s21, 28
	v_add_u32_e32 v10, s14, v5
	v_add_u32_e32 v13, s4, v7
	v_or_b32_e32 v17, s22, v1
	v_or_b32_e32 v48, s23, v4
	v_or_b32_e32 v49, s26, v1
	v_or_b32_e32 v50, s27, v4
	v_or_b32_e32 v51, s28, v1
	v_or_b32_e32 v52, s29, v4
	v_or_b32_e32 v53, s30, v1
	v_or_b32_e32 v54, s31, v4
	v_or_b32_e32 v55, s33, v1
	v_or_b32_e32 v56, s34, v4
	v_or_b32_e32 v57, s35, v1
	v_or_b32_e32 v58, s36, v4
	v_or_b32_e32 v59, s20, v1
	v_or_b32_e32 v60, s21, v4
	v_mul_lo_u32 v14, v13, s16
	v_mul_lo_u32 v18, v10, s16
	v_add_u32_e32 v10, s14, v17
	v_add_u32_e32 v13, s4, v48
	v_add_u32_e32 v21, s14, v49
	v_add_u32_e32 v23, s4, v50
	v_add_u32_e32 v25, s14, v51
	v_add_u32_e32 v27, s4, v52
	v_add_u32_e32 v29, s14, v53
	v_add_u32_e32 v31, s4, v54
	v_add_u32_e32 v33, s14, v55
	v_add_u32_e32 v35, s4, v56
	v_add_u32_e32 v37, s14, v57
	v_add_u32_e32 v39, s4, v58
	v_add_u32_e32 v41, s14, v59
	v_add_u32_e32 v43, s4, v60
	v_ashrrev_i32_e32 v15, 31, v14
	v_mul_lo_u32 v20, v13, s16
	v_mul_lo_u32 v22, v10, s16
	v_mul_lo_u32 v24, v23, s16
	v_mul_lo_u32 v26, v21, s16
	v_mul_lo_u32 v28, v27, s16
	v_mul_lo_u32 v30, v25, s16
	v_mul_lo_u32 v32, v31, s16
	v_mul_lo_u32 v34, v29, s16
	v_mul_lo_u32 v36, v35, s16
	v_mul_lo_u32 v38, v33, s16
	v_mul_lo_u32 v40, v39, s16
	v_mul_lo_u32 v42, v37, s16
	v_mul_lo_u32 v44, v43, s16
	v_mul_lo_u32 v46, v41, s16
	v_ashrrev_i32_e32 v19, 31, v18
	v_lshl_add_u64 v[14:15], v[14:15], 2, v[8:9]
	v_ashrrev_i32_e32 v23, 31, v22
	v_ashrrev_i32_e32 v21, 31, v20
	v_ashrrev_i32_e32 v27, 31, v26
	v_ashrrev_i32_e32 v25, 31, v24
	v_ashrrev_i32_e32 v31, 31, v30
	v_ashrrev_i32_e32 v29, 31, v28
	v_ashrrev_i32_e32 v35, 31, v34
	v_ashrrev_i32_e32 v33, 31, v32
	v_ashrrev_i32_e32 v39, 31, v38
	v_ashrrev_i32_e32 v37, 31, v36
	v_ashrrev_i32_e32 v43, 31, v42
	v_ashrrev_i32_e32 v41, 31, v40
	v_ashrrev_i32_e32 v47, 31, v46
	v_ashrrev_i32_e32 v45, 31, v44
	v_lshl_add_u64 v[18:19], v[18:19], 2, v[8:9]
	v_lshl_add_u64 v[20:21], v[20:21], 2, v[8:9]
	v_lshl_add_u64 v[22:23], v[22:23], 2, v[8:9]
	v_lshl_add_u64 v[24:25], v[24:25], 2, v[8:9]
	v_lshl_add_u64 v[26:27], v[26:27], 2, v[8:9]
	v_lshl_add_u64 v[28:29], v[28:29], 2, v[8:9]
	v_lshl_add_u64 v[30:31], v[30:31], 2, v[8:9]
	v_lshl_add_u64 v[32:33], v[32:33], 2, v[8:9]
	v_lshl_add_u64 v[34:35], v[34:35], 2, v[8:9]
	v_lshl_add_u64 v[36:37], v[36:37], 2, v[8:9]
	v_lshl_add_u64 v[38:39], v[38:39], 2, v[8:9]
	v_lshl_add_u64 v[40:41], v[40:41], 2, v[8:9]
	v_lshl_add_u64 v[42:43], v[42:43], 2, v[8:9]
	v_lshl_add_u64 v[44:45], v[44:45], 2, v[8:9]
	v_lshl_add_u64 v[46:47], v[46:47], 2, v[8:9]
	global_load_dword v10, v[14:15], off
	global_load_dword v13, v[18:19], off
	global_load_dword v61, v[20:21], off
	global_load_dword v62, v[22:23], off
	global_load_dword v63, v[24:25], off
	global_load_dword v64, v[26:27], off
	global_load_dword v65, v[28:29], off
	global_load_dword v66, v[30:31], off
	global_load_dword v67, v[32:33], off
	global_load_dword v68, v[34:35], off
	global_load_dword v69, v[36:37], off
	global_load_dword v70, v[38:39], off
	global_load_dword v71, v[40:41], off
	global_load_dword v72, v[42:43], off
	global_load_dword v73, v[44:45], off
	global_load_dword v74, v[46:47], off
	s_add_i32 s7, s7, 16
	s_add_i32 s6, s6, 16
	s_add_i32 s15, s15, -16
	v_mad_u64_u32 v[14:15], s[20:21], v7, s17, v[6:7]
	s_cmp_lg_u32 s15, 0
	v_mad_u64_u32 v[18:19], s[20:21], v5, s17, v[6:7]
	v_mad_u64_u32 v[20:21], s[20:21], v48, s17, v[6:7]
	v_mad_u64_u32 v[22:23], s[20:21], v17, s17, v[6:7]
	v_mad_u64_u32 v[24:25], s[20:21], v50, s17, v[6:7]
	v_mad_u64_u32 v[26:27], s[20:21], v49, s17, v[6:7]
	v_mad_u64_u32 v[28:29], s[20:21], v52, s17, v[6:7]
	v_mad_u64_u32 v[30:31], s[20:21], v51, s17, v[6:7]
	v_mad_u64_u32 v[32:33], s[20:21], v54, s17, v[6:7]
	v_mad_u64_u32 v[34:35], s[20:21], v53, s17, v[6:7]
	v_mad_u64_u32 v[36:37], s[20:21], v56, s17, v[6:7]
	v_mad_u64_u32 v[38:39], s[20:21], v55, s17, v[6:7]
	v_mad_u64_u32 v[40:41], s[20:21], v58, s17, v[6:7]
	v_mad_u64_u32 v[42:43], s[20:21], v57, s17, v[6:7]
	v_mad_u64_u32 v[44:45], s[20:21], v60, s17, v[6:7]
	v_mad_u64_u32 v[46:47], s[20:21], v59, s17, v[6:7]
	s_lshl_b32 s20, s6, 1
	s_lshl_b32 s21, s7, 1
	v_or_b32_e32 v105, s20, v1
	v_or_b32_e32 v107, s21, v4
	s_add_i32 s22, s20, 4
	s_add_i32 s23, s21, 4
	s_add_i32 s26, s20, 8
	s_add_i32 s27, s21, 8
	s_add_i32 s28, s20, 12
	s_add_i32 s29, s21, 12
	s_add_i32 s30, s20, 16
	s_add_i32 s31, s21, 16
	s_add_i32 s33, s20, 20
	s_add_i32 s34, s21, 20
	s_add_i32 s35, s20, 24
	s_add_i32 s36, s21, 24
	s_add_i32 s20, s20, 28
	s_add_i32 s21, s21, 28
	v_add_u32_e32 v110, s14, v105
	v_add_u32_e32 v113, s4, v107
	v_or_b32_e32 v117, s22, v1
	v_or_b32_e32 v148, s23, v4
	v_or_b32_e32 v149, s26, v1
	v_or_b32_e32 v150, s27, v4
	v_or_b32_e32 v151, s28, v1
	v_or_b32_e32 v152, s29, v4
	v_or_b32_e32 v153, s30, v1
	v_or_b32_e32 v154, s31, v4
	v_or_b32_e32 v155, s33, v1
	v_or_b32_e32 v156, s34, v4
	v_or_b32_e32 v157, s35, v1
	v_or_b32_e32 v158, s36, v4
	v_or_b32_e32 v159, s20, v1
	v_or_b32_e32 v160, s21, v4
	v_mul_lo_u32 v114, v113, s16
	v_mul_lo_u32 v118, v110, s16
	v_add_u32_e32 v110, s14, v117
	v_add_u32_e32 v113, s4, v148
	v_add_u32_e32 v121, s14, v149
	v_add_u32_e32 v123, s4, v150
	v_add_u32_e32 v125, s14, v151
	v_add_u32_e32 v127, s4, v152
; template <bool MAP> __device__ __forceinline__ void p0_transpose_item(const float* W, int K, int NS, bf16* WT, LAS float* scr, int item, int nkb, int lane) {
;     ...
;     for (int i = 0; i < 32; ++i) { const int kk = 2 * i + (lane >> 5); scr[kk * 33 + (lane & 31)] = W[(size_t)(k0 + kk) * NS + sc]; }
	v_add_u32_e32 v129, s14, v153
	v_add_u32_e32 v131, s4, v154
	v_add_u32_e32 v133, s14, v155
	v_add_u32_e32 v135, s4, v156
	v_add_u32_e32 v137, s14, v157
	v_add_u32_e32 v139, s4, v158
	v_add_u32_e32 v141, s14, v159
	v_add_u32_e32 v143, s4, v160
	v_ashrrev_i32_e32 v115, 31, v114
	v_mul_lo_u32 v120, v113, s16
	v_mul_lo_u32 v122, v110, s16
	v_mul_lo_u32 v124, v123, s16
	v_mul_lo_u32 v126, v121, s16
	v_mul_lo_u32 v128, v127, s16
	v_mul_lo_u32 v130, v125, s16
	v_mul_lo_u32 v132, v131, s16
	v_mul_lo_u32 v134, v129, s16
	v_mul_lo_u32 v136, v135, s16
	v_mul_lo_u32 v138, v133, s16
	v_mul_lo_u32 v140, v139, s16
	v_mul_lo_u32 v142, v137, s16
	v_mul_lo_u32 v144, v143, s16
	v_mul_lo_u32 v146, v141, s16
	v_ashrrev_i32_e32 v119, 31, v118
	v_lshl_add_u64 v[114:115], v[114:115], 2, v[8:9]
	v_ashrrev_i32_e32 v123, 31, v122
	v_ashrrev_i32_e32 v121, 31, v120
	v_ashrrev_i32_e32 v127, 31, v126
	v_ashrrev_i32_e32 v125, 31, v124
	v_ashrrev_i32_e32 v131, 31, v130
	v_ashrrev_i32_e32 v129, 31, v128
	v_ashrrev_i32_e32 v135, 31, v134
	v_ashrrev_i32_e32 v133, 31, v132
	v_ashrrev_i32_e32 v139, 31, v138
	v_ashrrev_i32_e32 v137, 31, v136
	v_ashrrev_i32_e32 v143, 31, v142
	v_ashrrev_i32_e32 v141, 31, v140
	v_ashrrev_i32_e32 v147, 31, v146
	v_ashrrev_i32_e32 v145, 31, v144
	v_lshl_add_u64 v[118:119], v[118:119], 2, v[8:9]
	v_lshl_add_u64 v[120:121], v[120:121], 2, v[8:9]
	v_lshl_add_u64 v[122:123], v[122:123], 2, v[8:9]
	v_lshl_add_u64 v[124:125], v[124:125], 2, v[8:9]
	v_lshl_add_u64 v[126:127], v[126:127], 2, v[8:9]
	v_lshl_add_u64 v[128:129], v[128:129], 2, v[8:9]
	v_lshl_add_u64 v[130:131], v[130:131], 2, v[8:9]
	v_lshl_add_u64 v[132:133], v[132:133], 2, v[8:9]
	v_lshl_add_u64 v[134:135], v[134:135], 2, v[8:9]
	v_lshl_add_u64 v[136:137], v[136:137], 2, v[8:9]
	v_lshl_add_u64 v[138:139], v[138:139], 2, v[8:9]
	v_lshl_add_u64 v[140:141], v[140:141], 2, v[8:9]
	v_lshl_add_u64 v[142:143], v[142:143], 2, v[8:9]
	v_lshl_add_u64 v[144:145], v[144:145], 2, v[8:9]
	v_lshl_add_u64 v[146:147], v[146:147], 2, v[8:9]
	global_load_dword v110, v[114:115], off
	global_load_dword v113, v[118:119], off
	global_load_dword v161, v[120:121], off
	global_load_dword v162, v[122:123], off
	global_load_dword v163, v[124:125], off
	global_load_dword v164, v[126:127], off
	global_load_dword v165, v[128:129], off
	global_load_dword v166, v[130:131], off
	global_load_dword v167, v[132:133], off
	global_load_dword v168, v[134:135], off
	global_load_dword v169, v[136:137], off
	global_load_dword v170, v[138:139], off
	global_load_dword v171, v[140:141], off
	global_load_dword v172, v[142:143], off
	global_load_dword v173, v[144:145], off
	global_load_dword v174, v[146:147], off
	s_waitcnt vmcnt(31)
	ds_write_b32 v14, v10
	s_waitcnt vmcnt(30)
	ds_write_b32 v18, v13
	s_waitcnt vmcnt(29)
	ds_write_b32 v20, v61
	s_waitcnt vmcnt(28)
	ds_write_b32 v22, v62
	s_waitcnt vmcnt(27)
	ds_write_b32 v24, v63
	s_waitcnt vmcnt(26)
	ds_write_b32 v26, v64
	s_waitcnt vmcnt(25)
	ds_write_b32 v28, v65
	s_waitcnt vmcnt(24)
	ds_write_b32 v30, v66
	s_waitcnt vmcnt(23)
	ds_write_b32 v32, v67
	s_waitcnt vmcnt(22)
	ds_write_b32 v34, v68
	s_waitcnt vmcnt(21)
	ds_write_b32 v36, v69
	s_waitcnt vmcnt(20)
	ds_write_b32 v38, v70
	s_waitcnt vmcnt(19)
	ds_write_b32 v40, v71
	s_waitcnt vmcnt(18)
	ds_write_b32 v42, v72
	s_waitcnt vmcnt(17)
	ds_write_b32 v44, v73
	s_waitcnt vmcnt(16)
	ds_write_b32 v46, v74
	s_add_i32 s7, s7, 16
	s_add_i32 s6, s6, 16
	s_add_i32 s15, s15, -16
	v_mad_u64_u32 v[14:15], s[20:21], v107, s17, v[6:7]
	s_cmp_lg_u32 s15, 0
	v_mad_u64_u32 v[18:19], s[20:21], v105, s17, v[6:7]
	v_mad_u64_u32 v[20:21], s[20:21], v148, s17, v[6:7]
	v_mad_u64_u32 v[22:23], s[20:21], v117, s17, v[6:7]
	v_mad_u64_u32 v[24:25], s[20:21], v150, s17, v[6:7]
	v_mad_u64_u32 v[26:27], s[20:21], v149, s17, v[6:7]
	v_mad_u64_u32 v[28:29], s[20:21], v152, s17, v[6:7]
	v_mad_u64_u32 v[30:31], s[20:21], v151, s17, v[6:7]
	v_mad_u64_u32 v[32:33], s[20:21], v154, s17, v[6:7]
	v_mad_u64_u32 v[34:35], s[20:21], v153, s17, v[6:7]
	v_mad_u64_u32 v[36:37], s[20:21], v156, s17, v[6:7]
	v_mad_u64_u32 v[38:39], s[20:21], v155, s17, v[6:7]
	v_mad_u64_u32 v[40:41], s[20:21], v158, s17, v[6:7]
	v_mad_u64_u32 v[42:43], s[20:21], v157, s17, v[6:7]
	v_mad_u64_u32 v[44:45], s[20:21], v160, s17, v[6:7]
	v_mad_u64_u32 v[46:47], s[20:21], v159, s17, v[6:7]
	s_waitcnt vmcnt(15)
; #define GAS __attribute__((address_space(1)))
; #define LAS __attribute__((address_space(3)))
; #define LDS_WAIT() asm volatile("s_waitcnt lgkmcnt(0)" ::: "memory")
; __device__ __forceinline__ unsigned pk2(float lo, float hi) { return pg8::cvt_pk_bf16(lo, hi); }
; __host__ __device__ __forceinline__ int proj_src_col(int p) {
;     const int pn = p >> 8, r = p & 255, bj = r >> 7, wc = (r >> 5) & 3, jj = r & 31;
;     if (pn >= 8 && pn < 16) { const int fq = jj >> 3, n = (jj >> 2) & 1, i = jj & 3; const int sect = bj == 0 ? (n == 0 ? 2056 : 2568) : (n == 0 ? 3080 : 3592); return sect + 64 * (pn - 8) + 16 * wc + 4 * fq + i; }
;     if (pn >= 16) return (bj == 0 ? 4104 : 5128) + 128 * (pn - 16) + 32 * wc + jj;
;     const int nat = 64 * wc + 32 * bj + jj;
;     if (pn < 6) return 256 * pn + nat;
;     return 1544 + 256 * (pn - 6) + nat;
; template <bool MAP> __device__ __forceinline__ void p0_transpose_item(const float* W, int K, int NS, bf16* WT, LAS float* scr, int item, int nkb, int lane) {
;     ...
;     for (int i = 0; i < 32; ++i) { const int kk = 2 * i + (lane >> 5); scr[kk * 33 + (lane & 31)] = W[(size_t)(k0 + kk) * NS + sc]; }
;     LDS_WAIT(); asm volatile("" ::: "memory");
;     const int c = lane & 7;
; #pragma unroll
;     for (int j = 0; j < 4; ++j) { const int n = (lane >> 3) + 8 * j; const LAS float* s = scr + (8 * c) * 33 + n;
;         v4u o; o.x = pk2(s[0 * 33], s[1 * 33]); o.y = pk2(s[2 * 33], s[3 * 33]); o.z = pk2(s[4 * 33], s[5 * 33]); o.w = pk2(s[6 * 33], s[7 * 33]);
;         *(GAS v4u*)(WT + (size_t)(p0 + n) * K + k0 + 8 * c) = o; }
;     LDS_WAIT(); asm volatile("" ::: "memory");
	ds_write_b32 v14, v110
	s_waitcnt vmcnt(14)
	ds_write_b32 v18, v113
	s_waitcnt vmcnt(13)
	ds_write_b32 v20, v161
	s_waitcnt vmcnt(12)
	ds_write_b32 v22, v162
	s_waitcnt vmcnt(11)
	ds_write_b32 v24, v163
	s_waitcnt vmcnt(10)
	ds_write_b32 v26, v164
	s_waitcnt vmcnt(9)
	ds_write_b32 v28, v165
	s_waitcnt vmcnt(8)
	ds_write_b32 v30, v166
	s_waitcnt vmcnt(7)
	ds_write_b32 v32, v167
	s_waitcnt vmcnt(6)
	ds_write_b32 v34, v168
	s_waitcnt vmcnt(5)
	ds_write_b32 v36, v169
	s_waitcnt vmcnt(4)
	ds_write_b32 v38, v170
	s_waitcnt vmcnt(3)
	ds_write_b32 v40, v171
	s_waitcnt vmcnt(2)
	ds_write_b32 v42, v172
	s_waitcnt vmcnt(1)
	ds_write_b32 v44, v173
	s_waitcnt vmcnt(0)
	ds_write_b32 v46, v174
	v_lshlrev_b32_e32 v5, 3, v16
	v_lshrrev_b32_e32 v7, 3, v16
	v_and_b32_e32 v10, 56, v5
	s_waitcnt lgkmcnt(0)
	v_mul_u32_u24_e32 v5, 0x84, v10
	v_lshlrev_b32_e32 v8, 2, v7
	v_add3_u32 v5, s5, v5, v8
	ds_read2_b32 v[8:9], v5 offset1:33
	s_add_u32 s7, s10, 0x200000
	s_waitcnt lgkmcnt(0)
	v_cvt_pk_bf16_f32 v14, v8, v9
	ds_read2_b32 v[8:9], v5 offset0:66 offset1:99
	s_waitcnt lgkmcnt(0)
	v_cvt_pk_bf16_f32 v15, v8, v9
	ds_read2_b32 v[16:17], v5 offset0:132 offset1:165
	s_addc_u32 s6, s11, 0
	s_ashr_i32 s5, s4, 31
	s_lshl_b64 s[4:5], s[4:5], 1
	s_waitcnt lgkmcnt(0)
	v_cvt_pk_bf16_f32 v16, v16, v17
	ds_read2_b32 v[18:19], v5 offset0:198 offset1:231
	s_add_u32 s4, s7, s4
	s_waitcnt lgkmcnt(0)
	v_cvt_pk_bf16_f32 v17, v18, v19
	v_or_b32_e32 v18, s12, v7
	v_mov_b32_e32 v9, 0
	v_lshlrev_b32_e32 v8, 1, v10
	s_addc_u32 s5, s6, s5
	v_ashrrev_i32_e32 v19, 31, v18
	v_lshl_add_u64 v[20:21], s[4:5], 0, v[8:9]
	v_lshlrev_b64 v[18:19], 11, v[18:19]
	v_lshl_add_u64 v[18:19], v[20:21], 0, v[18:19]
	ds_read2_b32 v[22:23], v5 offset0:8 offset1:41
	global_store_dwordx4 v[18:19], v[14:17], off
	v_or_b32_e32 v13, 24, v7
	v_or_b32_e32 v26, s12, v13
	s_waitcnt lgkmcnt(0)
	v_cvt_pk_bf16_f32 v16, v22, v23
	ds_read2_b32 v[14:15], v5 offset0:74 offset1:107
	s_waitcnt lgkmcnt(0)
	v_cvt_pk_bf16_f32 v17, v14, v15
	ds_read2_b32 v[14:15], v5 offset0:140 offset1:173
	s_waitcnt lgkmcnt(0)
	v_cvt_pk_bf16_f32 v18, v14, v15
	v_or_b32_e32 v15, 8, v7
	v_or_b32_e32 v24, s12, v15
	v_ashrrev_i32_e32 v25, 31, v24
	v_lshlrev_b64 v[24:25], 11, v[24:25]
	ds_read2_b32 v[22:23], v5 offset0:206 offset1:239
	s_waitcnt lgkmcnt(0)
	v_cvt_pk_bf16_f32 v19, v22, v23
	v_lshl_add_u64 v[24:25], v[20:21], 0, v[24:25]
	v_or_b32_e32 v14, 16, v7
	ds_read2_b32 v[22:23], v5 offset0:16 offset1:49
	global_store_dwordx4 v[24:25], v[16:19], off
	v_or_b32_e32 v24, s12, v14
	v_ashrrev_i32_e32 v25, 31, v24
	s_waitcnt lgkmcnt(0)
	v_cvt_pk_bf16_f32 v16, v22, v23
	ds_read2_b32 v[18:19], v5 offset0:82 offset1:115
	s_waitcnt lgkmcnt(0)
	v_cvt_pk_bf16_f32 v17, v18, v19
	ds_read2_b32 v[18:19], v5 offset0:148 offset1:181
	s_waitcnt lgkmcnt(0)
	v_cvt_pk_bf16_f32 v18, v18, v19
	ds_read2_b32 v[22:23], v5 offset0:214 offset1:247
	v_lshlrev_b64 v[24:25], 11, v[24:25]
	s_waitcnt lgkmcnt(0)
	v_cvt_pk_bf16_f32 v19, v22, v23
	ds_read2_b32 v[22:23], v5 offset0:24 offset1:57
	v_ashrrev_i32_e32 v27, 31, v26
	v_lshl_add_u64 v[24:25], v[20:21], 0, v[24:25]
	global_store_dwordx4 v[24:25], v[16:19], off
	s_add_i32 s11, s13, 0xa00
	s_ashr_i32 s4, s11, 31
	s_waitcnt lgkmcnt(0)
	v_cvt_pk_bf16_f32 v16, v22, v23
	ds_read2_b32 v[18:19], v5 offset0:90 offset1:123
	v_lshlrev_b64 v[22:23], 11, v[26:27]
	v_lshl_add_u64 v[20:21], v[20:21], 0, v[22:23]
	s_waitcnt lgkmcnt(0)
	v_cvt_pk_bf16_f32 v17, v18, v19
	ds_read2_b32 v[18:19], v5 offset0:156 offset1:189
	s_lshr_b32 s4, s4, 28
	s_waitcnt lgkmcnt(0)
	v_cvt_pk_bf16_f32 v18, v18, v19
	ds_read2_b32 v[22:23], v5 offset0:222 offset1:255
	s_waitcnt lgkmcnt(0)
	v_cvt_pk_bf16_f32 v19, v22, v23
	global_store_dwordx4 v[20:21], v[16:19], off
	s_add_i32 s4, s11, s4
	s_waitcnt lgkmcnt(0)
	s_ashr_i32 s12, s4, 4
	s_ashr_i32 s13, s4, 7
	s_lshl_b32 s10, s12, 5
	s_bfe_u32 s15, s12, 0x10002
	s_and_b32 s14, s12, 3
	s_and_b32 s4, s12, 0x7ffffc0
	s_cmp_lg_u32 s4, 64
	s_cbranch_scc0 .LBB0_62
	s_cmp_lt_i32 s13, 16
	s_cbranch_scc0 .LBB0_63
	s_lshl_b32 s4, s14, 6
	s_lshl_b32 s5, s15, 5
	s_or_b32 s4, s5, s4
	s_and_b32 s16, s10, 0xffffff00
	s_cmp_gt_i32 s13, 5
	v_or_b32_e32 v9, s4, v3
	s_cbranch_scc0 .LBB0_64
	v_add3_u32 v10, v9, s16, 8
	s_cbranch_execz .LBB0_65
	s_branch .LBB0_66

; #define LAS __attribute__((address_space(3)))
; template <bool MAP> __device__ __forceinline__ void p0_transpose_item(const float* W, int K, int NS, bf16* WT, LAS float* scr, int item, int nkb, int lane) {
;     const int pb = item / nkb, kb = item % nkb, k0 = 64 * kb, p0 = 32 * pb;
;     const int sc = MAP ? pg8::proj_src_col(p0 + (lane & 31)) : p0 + (lane & 31);
; #pragma unroll 8
;     for (int i = 0; i < 32; ++i) { const int kk = 2 * i + (lane >> 5); scr[kk * 33 + (lane & 31)] = W[(size_t)(k0 + kk) * NS + sc]; }
.LBB0_71:
	s_lshl_b32 s14, s8, 1
	s_lshl_b32 s15, s9, 1
	v_or_b32_e32 v9, s14, v1
	v_or_b32_e32 v12, s15, v4
	s_add_i32 s16, s14, 4
	s_add_i32 s17, s15, 4
	s_add_i32 s20, s14, 8
	s_add_i32 s21, s15, 8
	s_add_i32 s22, s14, 12
	s_add_i32 s23, s15, 12
	s_add_i32 s26, s14, 16
	s_add_i32 s27, s15, 16
	s_add_i32 s28, s14, 20
	s_add_i32 s29, s15, 20
	s_add_i32 s30, s14, 24
	s_add_i32 s31, s15, 24
	s_add_i32 s14, s14, 28
	s_add_i32 s15, s15, 28
	v_add_u32_e32 v10, s4, v12
	v_or_b32_e32 v46, s16, v1
	v_or_b32_e32 v47, s17, v4
	v_or_b32_e32 v48, s20, v1
	v_or_b32_e32 v49, s21, v4
	v_or_b32_e32 v50, s22, v1
	v_or_b32_e32 v51, s23, v4
	v_or_b32_e32 v52, s26, v1
	v_or_b32_e32 v53, s27, v4
	v_or_b32_e32 v54, s28, v1
	v_or_b32_e32 v55, s29, v4
	v_or_b32_e32 v56, s30, v1
	v_or_b32_e32 v57, s31, v4
	v_or_b32_e32 v58, s14, v1
	v_or_b32_e32 v59, s15, v4
	v_add_u32_e32 v11, s5, v9
	v_mul_lo_u32 v10, v10, s12
	v_add_u32_e32 v19, s5, v46
	v_add_u32_e32 v18, s4, v47
	v_add_u32_e32 v21, s5, v48
	v_add_u32_e32 v22, s4, v49
	v_add_u32_e32 v23, s5, v50
	v_add_u32_e32 v25, s4, v51
	v_add_u32_e32 v27, s5, v52
	v_add_u32_e32 v29, s4, v53
	v_add_u32_e32 v31, s5, v54
	v_add_u32_e32 v33, s4, v55
	v_add_u32_e32 v35, s5, v56
	v_add_u32_e32 v37, s4, v57
	v_add_u32_e32 v39, s5, v58
	v_add_u32_e32 v41, s4, v59
	v_mul_lo_u32 v16, v11, s12
	v_ashrrev_i32_e32 v11, 31, v10
	v_mul_lo_u32 v18, v18, s12
	v_mul_lo_u32 v20, v19, s12
	v_mul_lo_u32 v22, v22, s12
	v_mul_lo_u32 v24, v21, s12
	v_mul_lo_u32 v26, v25, s12
	v_mul_lo_u32 v28, v23, s12
	v_mul_lo_u32 v30, v29, s12
	v_mul_lo_u32 v32, v27, s12
	v_mul_lo_u32 v34, v33, s12
	v_mul_lo_u32 v36, v31, s12
	v_mul_lo_u32 v38, v37, s12
	v_mul_lo_u32 v40, v35, s12
	v_mul_lo_u32 v42, v41, s12
	v_mul_lo_u32 v44, v39, s12
	v_ashrrev_i32_e32 v17, 31, v16
	v_lshl_add_u64 v[10:11], v[10:11], 2, v[2:3]
	v_ashrrev_i32_e32 v21, 31, v20
	v_ashrrev_i32_e32 v19, 31, v18
	v_ashrrev_i32_e32 v25, 31, v24
	v_ashrrev_i32_e32 v23, 31, v22
	v_ashrrev_i32_e32 v29, 31, v28
	v_ashrrev_i32_e32 v27, 31, v26
	v_ashrrev_i32_e32 v33, 31, v32
	v_ashrrev_i32_e32 v31, 31, v30
	v_ashrrev_i32_e32 v37, 31, v36
	v_ashrrev_i32_e32 v35, 31, v34
	v_ashrrev_i32_e32 v41, 31, v40
	v_ashrrev_i32_e32 v39, 31, v38
	v_ashrrev_i32_e32 v45, 31, v44
	v_ashrrev_i32_e32 v43, 31, v42
	v_lshl_add_u64 v[16:17], v[16:17], 2, v[2:3]
	v_lshl_add_u64 v[18:19], v[18:19], 2, v[2:3]
	v_lshl_add_u64 v[20:21], v[20:21], 2, v[2:3]
	v_lshl_add_u64 v[22:23], v[22:23], 2, v[2:3]
	v_lshl_add_u64 v[24:25], v[24:25], 2, v[2:3]
	v_lshl_add_u64 v[26:27], v[26:27], 2, v[2:3]
	v_lshl_add_u64 v[28:29], v[28:29], 2, v[2:3]
	v_lshl_add_u64 v[30:31], v[30:31], 2, v[2:3]
	v_lshl_add_u64 v[32:33], v[32:33], 2, v[2:3]
	v_lshl_add_u64 v[34:35], v[34:35], 2, v[2:3]
	v_lshl_add_u64 v[36:37], v[36:37], 2, v[2:3]
	v_lshl_add_u64 v[38:39], v[38:39], 2, v[2:3]
	v_lshl_add_u64 v[40:41], v[40:41], 2, v[2:3]
	v_lshl_add_u64 v[42:43], v[42:43], 2, v[2:3]
	v_lshl_add_u64 v[44:45], v[44:45], 2, v[2:3]
	global_load_dword v60, v[10:11], off
	global_load_dword v61, v[16:17], off
	global_load_dword v62, v[18:19], off
	global_load_dword v63, v[20:21], off
	global_load_dword v64, v[22:23], off
	global_load_dword v65, v[24:25], off
	global_load_dword v66, v[26:27], off
	global_load_dword v67, v[28:29], off
	global_load_dword v68, v[30:31], off
	global_load_dword v69, v[32:33], off
	global_load_dword v70, v[34:35], off
	global_load_dword v71, v[36:37], off
	global_load_dword v72, v[38:39], off
	global_load_dword v73, v[40:41], off
	global_load_dword v74, v[42:43], off
	global_load_dword v75, v[44:45], off
	s_add_i32 s9, s9, 16
	s_add_i32 s8, s8, 16
	s_add_i32 s11, s11, -16
	v_mad_u64_u32 v[10:11], s[14:15], v12, s13, v[6:7]
	s_cmp_lg_u32 s11, 0
	v_mad_u64_u32 v[16:17], s[14:15], v9, s13, v[6:7]
	v_mad_u64_u32 v[18:19], s[14:15], v47, s13, v[6:7]
	v_mad_u64_u32 v[20:21], s[14:15], v46, s13, v[6:7]
	v_mad_u64_u32 v[22:23], s[14:15], v49, s13, v[6:7]
	v_mad_u64_u32 v[24:25], s[14:15], v48, s13, v[6:7]
	v_mad_u64_u32 v[26:27], s[14:15], v51, s13, v[6:7]
	v_mad_u64_u32 v[28:29], s[14:15], v50, s13, v[6:7]
	v_mad_u64_u32 v[30:31], s[14:15], v53, s13, v[6:7]
	v_mad_u64_u32 v[32:33], s[14:15], v52, s13, v[6:7]
	v_mad_u64_u32 v[34:35], s[14:15], v55, s13, v[6:7]
	v_mad_u64_u32 v[36:37], s[14:15], v54, s13, v[6:7]
	v_mad_u64_u32 v[38:39], s[14:15], v57, s13, v[6:7]
	v_mad_u64_u32 v[40:41], s[14:15], v56, s13, v[6:7]
	v_mad_u64_u32 v[42:43], s[14:15], v59, s13, v[6:7]
	v_mad_u64_u32 v[44:45], s[14:15], v58, s13, v[6:7]
	s_lshl_b32 s14, s8, 1
	s_lshl_b32 s15, s9, 1
	v_or_b32_e32 v109, s14, v1
	v_or_b32_e32 v112, s15, v4
	s_add_i32 s16, s14, 4
	s_add_i32 s17, s15, 4
	s_add_i32 s20, s14, 8
	s_add_i32 s21, s15, 8
	s_add_i32 s22, s14, 12
	s_add_i32 s23, s15, 12
	s_add_i32 s26, s14, 16
	s_add_i32 s27, s15, 16
	s_add_i32 s28, s14, 20
	s_add_i32 s29, s15, 20
	s_add_i32 s30, s14, 24
	s_add_i32 s31, s15, 24
	s_add_i32 s14, s14, 28
	s_add_i32 s15, s15, 28
	v_add_u32_e32 v110, s4, v112
	v_or_b32_e32 v146, s16, v1
	v_or_b32_e32 v147, s17, v4
	v_or_b32_e32 v148, s20, v1
	v_or_b32_e32 v149, s21, v4
	v_or_b32_e32 v150, s22, v1
	v_or_b32_e32 v151, s23, v4
	v_or_b32_e32 v152, s26, v1
	v_or_b32_e32 v153, s27, v4
	v_or_b32_e32 v154, s28, v1
	v_or_b32_e32 v155, s29, v4
	v_or_b32_e32 v156, s30, v1
	v_or_b32_e32 v157, s31, v4
	v_or_b32_e32 v158, s14, v1
	v_or_b32_e32 v159, s15, v4
	v_add_u32_e32 v111, s5, v109
	v_mul_lo_u32 v110, v110, s12
	v_add_u32_e32 v119, s5, v146
	v_add_u32_e32 v118, s4, v147
	v_add_u32_e32 v121, s5, v148
	v_add_u32_e32 v122, s4, v149
	v_add_u32_e32 v123, s5, v150
	v_add_u32_e32 v125, s4, v151
	v_add_u32_e32 v127, s5, v152
	v_add_u32_e32 v129, s4, v153
; template <bool MAP> __device__ __forceinline__ void p0_transpose_item(const float* W, int K, int NS, bf16* WT, LAS float* scr, int item, int nkb, int lane) {
;     ...
;     for (int i = 0; i < 32; ++i) { const int kk = 2 * i + (lane >> 5); scr[kk * 33 + (lane & 31)] = W[(size_t)(k0 + kk) * NS + sc]; }
	v_add_u32_e32 v131, s5, v154
	v_add_u32_e32 v133, s4, v155
	v_add_u32_e32 v135, s5, v156
	v_add_u32_e32 v137, s4, v157
	v_add_u32_e32 v139, s5, v158
	v_add_u32_e32 v141, s4, v159
	v_mul_lo_u32 v116, v111, s12
	v_ashrrev_i32_e32 v111, 31, v110
	v_mul_lo_u32 v118, v118, s12
	v_mul_lo_u32 v120, v119, s12
	v_mul_lo_u32 v122, v122, s12
	v_mul_lo_u32 v124, v121, s12
	v_mul_lo_u32 v126, v125, s12
	v_mul_lo_u32 v128, v123, s12
	v_mul_lo_u32 v130, v129, s12
	v_mul_lo_u32 v132, v127, s12
	v_mul_lo_u32 v134, v133, s12
	v_mul_lo_u32 v136, v131, s12
	v_mul_lo_u32 v138, v137, s12
	v_mul_lo_u32 v140, v135, s12
	v_mul_lo_u32 v142, v141, s12
	v_mul_lo_u32 v144, v139, s12
	v_ashrrev_i32_e32 v117, 31, v116
	v_lshl_add_u64 v[110:111], v[110:111], 2, v[2:3]
	v_ashrrev_i32_e32 v121, 31, v120
	v_ashrrev_i32_e32 v119, 31, v118
	v_ashrrev_i32_e32 v125, 31, v124
	v_ashrrev_i32_e32 v123, 31, v122
	v_ashrrev_i32_e32 v129, 31, v128
	v_ashrrev_i32_e32 v127, 31, v126
	v_ashrrev_i32_e32 v133, 31, v132
	v_ashrrev_i32_e32 v131, 31, v130
	v_ashrrev_i32_e32 v137, 31, v136
	v_ashrrev_i32_e32 v135, 31, v134
	v_ashrrev_i32_e32 v141, 31, v140
	v_ashrrev_i32_e32 v139, 31, v138
	v_ashrrev_i32_e32 v145, 31, v144
	v_ashrrev_i32_e32 v143, 31, v142
	v_lshl_add_u64 v[116:117], v[116:117], 2, v[2:3]
	v_lshl_add_u64 v[118:119], v[118:119], 2, v[2:3]
	v_lshl_add_u64 v[120:121], v[120:121], 2, v[2:3]
	v_lshl_add_u64 v[122:123], v[122:123], 2, v[2:3]
	v_lshl_add_u64 v[124:125], v[124:125], 2, v[2:3]
	v_lshl_add_u64 v[126:127], v[126:127], 2, v[2:3]
	v_lshl_add_u64 v[128:129], v[128:129], 2, v[2:3]
	v_lshl_add_u64 v[130:131], v[130:131], 2, v[2:3]
	v_lshl_add_u64 v[132:133], v[132:133], 2, v[2:3]
	v_lshl_add_u64 v[134:135], v[134:135], 2, v[2:3]
	v_lshl_add_u64 v[136:137], v[136:137], 2, v[2:3]
	v_lshl_add_u64 v[138:139], v[138:139], 2, v[2:3]
	v_lshl_add_u64 v[140:141], v[140:141], 2, v[2:3]
	v_lshl_add_u64 v[142:143], v[142:143], 2, v[2:3]
	v_lshl_add_u64 v[144:145], v[144:145], 2, v[2:3]
	global_load_dword v160, v[110:111], off
	global_load_dword v161, v[116:117], off
	global_load_dword v162, v[118:119], off
	global_load_dword v163, v[120:121], off
	global_load_dword v164, v[122:123], off
	global_load_dword v165, v[124:125], off
	global_load_dword v166, v[126:127], off
	global_load_dword v167, v[128:129], off
	global_load_dword v168, v[130:131], off
	global_load_dword v169, v[132:133], off
	global_load_dword v170, v[134:135], off
	global_load_dword v171, v[136:137], off
	global_load_dword v172, v[138:139], off
	global_load_dword v173, v[140:141], off
	global_load_dword v174, v[142:143], off
	global_load_dword v175, v[144:145], off
	s_waitcnt vmcnt(31)
	ds_write_b32 v10, v60
	s_waitcnt vmcnt(30)
	ds_write_b32 v16, v61
	s_waitcnt vmcnt(29)
	ds_write_b32 v18, v62
	s_waitcnt vmcnt(28)
	ds_write_b32 v20, v63
	s_waitcnt vmcnt(27)
	ds_write_b32 v22, v64
	s_waitcnt vmcnt(26)
	ds_write_b32 v24, v65
	s_waitcnt vmcnt(25)
	ds_write_b32 v26, v66
	s_waitcnt vmcnt(24)
	ds_write_b32 v28, v67
	s_waitcnt vmcnt(23)
	ds_write_b32 v30, v68
	s_waitcnt vmcnt(22)
	ds_write_b32 v32, v69
	s_waitcnt vmcnt(21)
	ds_write_b32 v34, v70
	s_waitcnt vmcnt(20)
	ds_write_b32 v36, v71
	s_waitcnt vmcnt(19)
	ds_write_b32 v38, v72
	s_waitcnt vmcnt(18)
	ds_write_b32 v40, v73
	s_waitcnt vmcnt(17)
	ds_write_b32 v42, v74
	s_waitcnt vmcnt(16)
; #define GAS __attribute__((address_space(1)))
; #define LAS __attribute__((address_space(3)))
; #define LDS_WAIT() asm volatile("s_waitcnt lgkmcnt(0)" ::: "memory")
; __device__ __forceinline__ unsigned pk2(float lo, float hi) { return pg8::cvt_pk_bf16(lo, hi); }
; template <bool MAP> __device__ __forceinline__ void p0_transpose_item(const float* W, int K, int NS, bf16* WT, LAS float* scr, int item, int nkb, int lane) {
;     ...
;     for (int i = 0; i < 32; ++i) { const int kk = 2 * i + (lane >> 5); scr[kk * 33 + (lane & 31)] = W[(size_t)(k0 + kk) * NS + sc]; }
;     LDS_WAIT(); asm volatile("" ::: "memory");
;     const int c = lane & 7;
; #pragma unroll
;     for (int j = 0; j < 4; ++j) { const int n = (lane >> 3) + 8 * j; const LAS float* s = scr + (8 * c) * 33 + n;
;         v4u o; o.x = pk2(s[0 * 33], s[1 * 33]); o.y = pk2(s[2 * 33], s[3 * 33]); o.z = pk2(s[4 * 33], s[5 * 33]); o.w = pk2(s[6 * 33], s[7 * 33]);
;         *(GAS v4u*)(WT + (size_t)(p0 + n) * K + k0 + 8 * c) = o; }
;     LDS_WAIT(); asm volatile("" ::: "memory");
	ds_write_b32 v44, v75
	s_add_i32 s9, s9, 16
	s_add_i32 s8, s8, 16
	s_add_i32 s11, s11, -16
	v_mad_u64_u32 v[10:11], s[14:15], v112, s13, v[6:7]
	s_cmp_lg_u32 s11, 0
	v_mad_u64_u32 v[16:17], s[14:15], v109, s13, v[6:7]
	v_mad_u64_u32 v[18:19], s[14:15], v147, s13, v[6:7]
	v_mad_u64_u32 v[20:21], s[14:15], v146, s13, v[6:7]
	v_mad_u64_u32 v[22:23], s[14:15], v149, s13, v[6:7]
	v_mad_u64_u32 v[24:25], s[14:15], v148, s13, v[6:7]
	v_mad_u64_u32 v[26:27], s[14:15], v151, s13, v[6:7]
	v_mad_u64_u32 v[28:29], s[14:15], v150, s13, v[6:7]
	v_mad_u64_u32 v[30:31], s[14:15], v153, s13, v[6:7]
	v_mad_u64_u32 v[32:33], s[14:15], v152, s13, v[6:7]
	v_mad_u64_u32 v[34:35], s[14:15], v155, s13, v[6:7]
	v_mad_u64_u32 v[36:37], s[14:15], v154, s13, v[6:7]
	v_mad_u64_u32 v[38:39], s[14:15], v157, s13, v[6:7]
	v_mad_u64_u32 v[40:41], s[14:15], v156, s13, v[6:7]
	v_mad_u64_u32 v[42:43], s[14:15], v159, s13, v[6:7]
	v_mad_u64_u32 v[44:45], s[14:15], v158, s13, v[6:7]
	s_waitcnt vmcnt(15)
	ds_write_b32 v10, v160
	s_waitcnt vmcnt(14)
	ds_write_b32 v16, v161
	s_waitcnt vmcnt(13)
	ds_write_b32 v18, v162
	s_waitcnt vmcnt(12)
	ds_write_b32 v20, v163
	s_waitcnt vmcnt(11)
	ds_write_b32 v22, v164
	s_waitcnt vmcnt(10)
	ds_write_b32 v24, v165
	s_waitcnt vmcnt(9)
	ds_write_b32 v26, v166
	s_waitcnt vmcnt(8)
	ds_write_b32 v28, v167
	s_waitcnt vmcnt(7)
	ds_write_b32 v30, v168
	s_waitcnt vmcnt(6)
	ds_write_b32 v32, v169
	s_waitcnt vmcnt(5)
	ds_write_b32 v34, v170
	s_waitcnt vmcnt(4)
	ds_write_b32 v36, v171
	s_waitcnt vmcnt(3)
	ds_write_b32 v38, v172
	s_waitcnt vmcnt(2)
	ds_write_b32 v40, v173
	s_waitcnt vmcnt(1)
	ds_write_b32 v42, v174
	s_waitcnt vmcnt(0)
	ds_write_b32 v44, v175
	s_waitcnt lgkmcnt(0)
	s_ashr_i32 s5, s4, 31
	ds_read2_b32 v[2:3], v5 offset1:33
	s_lshl_b64 s[4:5], s[4:5], 1
	s_waitcnt lgkmcnt(0)
	v_cvt_pk_bf16_f32 v16, v2, v3
	ds_read2_b32 v[2:3], v5 offset0:66 offset1:99
	v_or_b32_e32 v6, s10, v7
	s_add_u32 s4, s7, s4
	s_waitcnt lgkmcnt(0)
	v_cvt_pk_bf16_f32 v17, v2, v3
	ds_read2_b32 v[2:3], v5 offset0:132 offset1:165
	v_mov_b32_e32 v9, 0
	v_ashrrev_i32_e32 v7, 31, v6
	s_addc_u32 s5, s6, s5
	s_waitcnt lgkmcnt(0)
	v_cvt_pk_bf16_f32 v18, v2, v3
	ds_read2_b32 v[2:3], v5 offset0:198 offset1:231
	v_lshlrev_b64 v[6:7], 11, v[6:7]
	v_lshl_add_u64 v[10:11], s[4:5], 0, v[8:9]
	s_waitcnt lgkmcnt(0)
	v_cvt_pk_bf16_f32 v19, v2, v3
	ds_read2_b32 v[2:3], v5 offset0:8 offset1:41
	v_lshl_add_u64 v[6:7], v[10:11], 0, v[6:7]
	global_store_dwordx4 v[6:7], v[16:19], off
	s_waitcnt lgkmcnt(0)
	v_cvt_pk_bf16_f32 v6, v2, v3
	ds_read2_b32 v[2:3], v5 offset0:74 offset1:107
	s_waitcnt lgkmcnt(0)
	v_cvt_pk_bf16_f32 v7, v2, v3
	ds_read2_b32 v[2:3], v5 offset0:140 offset1:173
	v_or_b32_e32 v16, s10, v15
	v_ashrrev_i32_e32 v17, 31, v16
	s_waitcnt lgkmcnt(0)
	v_cvt_pk_bf16_f32 v8, v2, v3
	ds_read2_b32 v[2:3], v5 offset0:206 offset1:239
	v_lshlrev_b64 v[16:17], 11, v[16:17]
	s_waitcnt lgkmcnt(0)
	v_cvt_pk_bf16_f32 v9, v2, v3
	ds_read2_b32 v[2:3], v5 offset0:16 offset1:49
	v_lshl_add_u64 v[16:17], v[10:11], 0, v[16:17]
	global_store_dwordx4 v[16:17], v[6:9], off
	v_or_b32_e32 v14, s10, v14
	v_ashrrev_i32_e32 v15, 31, v14
	s_waitcnt lgkmcnt(0)
	v_cvt_pk_bf16_f32 v6, v2, v3
	ds_read2_b32 v[2:3], v5 offset0:82 offset1:115
	s_waitcnt lgkmcnt(0)
	v_cvt_pk_bf16_f32 v7, v2, v3
	ds_read2_b32 v[2:3], v5 offset0:148 offset1:181
	s_waitcnt lgkmcnt(0)
	v_cvt_pk_bf16_f32 v8, v2, v3
	ds_read2_b32 v[2:3], v5 offset0:214 offset1:247
	v_lshlrev_b64 v[14:15], 11, v[14:15]
	s_waitcnt lgkmcnt(0)
	v_cvt_pk_bf16_f32 v9, v2, v3
	ds_read2_b32 v[2:3], v5 offset0:24 offset1:57
	v_lshl_add_u64 v[14:15], v[10:11], 0, v[14:15]
	global_store_dwordx4 v[14:15], v[6:9], off
	s_waitcnt lgkmcnt(0)
	v_cvt_pk_bf16_f32 v2, v2, v3
	ds_read2_b32 v[6:7], v5 offset0:90 offset1:123
	s_waitcnt lgkmcnt(0)
	v_cvt_pk_bf16_f32 v3, v6, v7
	ds_read2_b32 v[6:7], v5 offset0:156 offset1:189
	v_or_b32_e32 v8, s10, v13
	v_ashrrev_i32_e32 v9, 31, v8
	s_waitcnt lgkmcnt(0)
	v_cvt_pk_bf16_f32 v4, v6, v7
	ds_read2_b32 v[6:7], v5 offset0:222 offset1:255
	v_lshlrev_b64 v[8:9], 11, v[8:9]
	s_waitcnt lgkmcnt(0)
	v_cvt_pk_bf16_f32 v5, v6, v7
	v_lshl_add_u64 v[6:7], v[10:11], 0, v[8:9]
	global_store_dwordx4 v[6:7], v[2:5], off
	s_waitcnt lgkmcnt(0)

; #define LAS __attribute__((address_space(3)))
; template <bool MAP> __device__ __forceinline__ void p0_transpose_item(const float* W, int K, int NS, bf16* WT, LAS float* scr, int item, int nkb, int lane) {
;     const int pb = item / nkb, kb = item % nkb, k0 = 64 * kb, p0 = 32 * pb;
;     const int sc = MAP ? pg8::proj_src_col(p0 + (lane & 31)) : p0 + (lane & 31);
; #pragma unroll 8
;     for (int i = 0; i < 32; ++i) { const int kk = 2 * i + (lane >> 5); scr[kk * 33 + (lane & 31)] = W[(size_t)(k0 + kk) * NS + sc]; }
.LBB0_145:
	s_lshl_b32 s13, s10, 1
	s_lshl_b32 s14, s11, 1
	v_or_b32_e32 v17, s13, v1
	v_or_b32_e32 v34, s14, v2
	s_add_i32 s15, s13, 4
	s_add_i32 s16, s14, 4
	s_add_i32 s17, s13, 8
	s_add_i32 s20, s14, 8
	s_add_i32 s21, s13, 12
	s_add_i32 s26, s14, 12
	s_add_i32 s27, s13, 16
	s_add_i32 s28, s14, 16
	s_add_i32 s29, s13, 20
	s_add_i32 s30, s14, 20
	s_add_i32 s31, s13, 24
	s_add_i32 s34, s14, 24
	s_add_i32 s13, s13, 28
	s_add_i32 s14, s14, 28
	v_add_u32_e32 v18, s4, v34
	v_or_b32_e32 v52, s15, v1
	v_or_b32_e32 v53, s16, v2
	v_or_b32_e32 v54, s17, v1
	v_or_b32_e32 v55, s20, v2
	v_or_b32_e32 v56, s21, v1
	v_or_b32_e32 v57, s26, v2
	v_or_b32_e32 v58, s27, v1
	v_or_b32_e32 v59, s28, v2
	v_or_b32_e32 v60, s29, v1
	v_or_b32_e32 v61, s30, v2
	v_or_b32_e32 v62, s31, v1
	v_or_b32_e32 v63, s34, v2
	v_or_b32_e32 v64, s13, v1
	v_or_b32_e32 v65, s14, v2
	v_add_u32_e32 v19, s5, v17
	v_mul_lo_u32 v18, v18, s8
	v_add_u32_e32 v23, s5, v52
	v_add_u32_e32 v22, s4, v53
	v_add_u32_e32 v25, s5, v54
	v_add_u32_e32 v26, s4, v55
	v_add_u32_e32 v27, s5, v56
	v_add_u32_e32 v29, s4, v57
	v_add_u32_e32 v31, s5, v58
	v_add_u32_e32 v33, s4, v59
	v_add_u32_e32 v37, s5, v60
	v_add_u32_e32 v39, s4, v61
	v_add_u32_e32 v41, s5, v62
	v_add_u32_e32 v43, s4, v63
	v_add_u32_e32 v45, s5, v64
	v_add_u32_e32 v47, s4, v65
	v_mul_lo_u32 v20, v19, s8
	v_ashrrev_i32_e32 v19, 31, v18
	v_mul_lo_u32 v22, v22, s8
	v_mul_lo_u32 v24, v23, s8
	v_mul_lo_u32 v26, v26, s8
	v_mul_lo_u32 v28, v25, s8
	v_mul_lo_u32 v30, v29, s8
	v_mul_lo_u32 v32, v27, s8
	v_mul_lo_u32 v36, v33, s8
	v_mul_lo_u32 v38, v31, s8
	v_mul_lo_u32 v40, v39, s8
	v_mul_lo_u32 v42, v37, s8
	v_mul_lo_u32 v44, v43, s8
	v_mul_lo_u32 v46, v41, s8
	v_mul_lo_u32 v48, v47, s8
	v_mul_lo_u32 v50, v45, s8
	v_ashrrev_i32_e32 v21, 31, v20
	v_lshl_add_u64 v[18:19], v[18:19], 2, v[8:9]
	v_ashrrev_i32_e32 v25, 31, v24
	v_ashrrev_i32_e32 v23, 31, v22
	v_ashrrev_i32_e32 v29, 31, v28
	v_ashrrev_i32_e32 v27, 31, v26
	v_ashrrev_i32_e32 v33, 31, v32
	v_ashrrev_i32_e32 v31, 31, v30
	v_ashrrev_i32_e32 v39, 31, v38
	v_ashrrev_i32_e32 v37, 31, v36
	v_ashrrev_i32_e32 v43, 31, v42
	v_ashrrev_i32_e32 v41, 31, v40
	v_ashrrev_i32_e32 v47, 31, v46
	v_ashrrev_i32_e32 v45, 31, v44
	v_ashrrev_i32_e32 v51, 31, v50
	v_ashrrev_i32_e32 v49, 31, v48
	v_lshl_add_u64 v[20:21], v[20:21], 2, v[8:9]
	v_lshl_add_u64 v[22:23], v[22:23], 2, v[8:9]
	v_lshl_add_u64 v[24:25], v[24:25], 2, v[8:9]
	v_lshl_add_u64 v[26:27], v[26:27], 2, v[8:9]
	v_lshl_add_u64 v[28:29], v[28:29], 2, v[8:9]
	v_lshl_add_u64 v[30:31], v[30:31], 2, v[8:9]
	v_lshl_add_u64 v[32:33], v[32:33], 2, v[8:9]
	v_lshl_add_u64 v[36:37], v[36:37], 2, v[8:9]
	v_lshl_add_u64 v[38:39], v[38:39], 2, v[8:9]
	v_lshl_add_u64 v[40:41], v[40:41], 2, v[8:9]
	v_lshl_add_u64 v[42:43], v[42:43], 2, v[8:9]
	v_lshl_add_u64 v[44:45], v[44:45], 2, v[8:9]
	v_lshl_add_u64 v[46:47], v[46:47], 2, v[8:9]
	v_lshl_add_u64 v[48:49], v[48:49], 2, v[8:9]
	v_lshl_add_u64 v[50:51], v[50:51], 2, v[8:9]
	global_load_dword v66, v[18:19], off
	global_load_dword v67, v[20:21], off
	global_load_dword v69, v[22:23], off
	global_load_dword v70, v[24:25], off
	global_load_dword v71, v[26:27], off
	global_load_dword v72, v[28:29], off
	global_load_dword v73, v[30:31], off
	global_load_dword v74, v[32:33], off
	global_load_dword v75, v[36:37], off
	global_load_dword v76, v[38:39], off
	global_load_dword v77, v[40:41], off
	global_load_dword v78, v[42:43], off
	global_load_dword v79, v[44:45], off
	global_load_dword v80, v[46:47], off
	global_load_dword v81, v[48:49], off
	global_load_dword v82, v[50:51], off
	s_add_i32 s11, s11, 16
	s_add_i32 s10, s10, 16
	s_add_i32 s12, s12, -16
	v_mad_u64_u32 v[18:19], s[14:15], v34, s7, v[4:5]
	s_cmp_lg_u32 s12, 0
	v_mad_u64_u32 v[20:21], s[14:15], v17, s7, v[4:5]
	v_mad_u64_u32 v[22:23], s[14:15], v53, s7, v[4:5]
	v_mad_u64_u32 v[24:25], s[14:15], v52, s7, v[4:5]
	v_mad_u64_u32 v[26:27], s[14:15], v55, s7, v[4:5]
	v_mad_u64_u32 v[28:29], s[14:15], v54, s7, v[4:5]
	v_mad_u64_u32 v[30:31], s[14:15], v57, s7, v[4:5]
	v_mad_u64_u32 v[32:33], s[14:15], v56, s7, v[4:5]
	v_mad_u64_u32 v[36:37], s[14:15], v59, s7, v[4:5]
	v_mad_u64_u32 v[38:39], s[14:15], v58, s7, v[4:5]
	v_mad_u64_u32 v[40:41], s[14:15], v61, s7, v[4:5]
	v_mad_u64_u32 v[42:43], s[14:15], v60, s7, v[4:5]
	v_mad_u64_u32 v[44:45], s[14:15], v63, s7, v[4:5]
	v_mad_u64_u32 v[46:47], s[14:15], v62, s7, v[4:5]
	v_mad_u64_u32 v[48:49], s[14:15], v65, s7, v[4:5]
	v_mad_u64_u32 v[50:51], s[14:15], v64, s7, v[4:5]
	s_lshl_b32 s13, s10, 1
	s_lshl_b32 s14, s11, 1
	v_or_b32_e32 v187, s13, v1
	v_or_b32_e32 v204, s14, v2
	s_add_i32 s15, s13, 4
	s_add_i32 s16, s14, 4
	s_add_i32 s17, s13, 8
	s_add_i32 s20, s14, 8
	s_add_i32 s21, s13, 12
	s_add_i32 s26, s14, 12
	s_add_i32 s27, s13, 16
	s_add_i32 s28, s14, 16
	s_add_i32 s29, s13, 20
	s_add_i32 s30, s14, 20
	s_add_i32 s31, s13, 24
	s_add_i32 s34, s14, 24
	s_add_i32 s13, s13, 28
	s_add_i32 s14, s14, 28
	v_add_u32_e32 v188, s4, v204
	v_or_b32_e32 v222, s15, v1
	v_or_b32_e32 v223, s16, v2
	v_or_b32_e32 v224, s17, v1
	v_or_b32_e32 v225, s20, v2
	v_or_b32_e32 v226, s21, v1
	v_or_b32_e32 v227, s26, v2
	v_or_b32_e32 v228, s27, v1
	v_or_b32_e32 v229, s28, v2
	v_or_b32_e32 v230, s29, v1
	v_or_b32_e32 v231, s30, v2
	v_or_b32_e32 v232, s31, v1
	v_or_b32_e32 v233, s34, v2
	v_or_b32_e32 v234, s13, v1
	v_or_b32_e32 v235, s14, v2
	v_add_u32_e32 v189, s5, v187
	v_mul_lo_u32 v188, v188, s8
	v_add_u32_e32 v193, s5, v222
	v_add_u32_e32 v192, s4, v223
	v_add_u32_e32 v195, s5, v224
	v_add_u32_e32 v196, s4, v225
	v_add_u32_e32 v197, s5, v226
	v_add_u32_e32 v199, s4, v227
	v_add_u32_e32 v201, s5, v228
	v_add_u32_e32 v203, s4, v229
; template <bool MAP> __device__ __forceinline__ void p0_transpose_item(const float* W, int K, int NS, bf16* WT, LAS float* scr, int item, int nkb, int lane) {
;     ...
;     for (int i = 0; i < 32; ++i) { const int kk = 2 * i + (lane >> 5); scr[kk * 33 + (lane & 31)] = W[(size_t)(k0 + kk) * NS + sc]; }
	v_add_u32_e32 v207, s5, v230
	v_add_u32_e32 v209, s4, v231
	v_add_u32_e32 v211, s5, v232
	v_add_u32_e32 v213, s4, v233
	v_add_u32_e32 v215, s5, v234
	v_add_u32_e32 v217, s4, v235
	v_mul_lo_u32 v190, v189, s8
	v_ashrrev_i32_e32 v189, 31, v188
	v_mul_lo_u32 v192, v192, s8
	v_mul_lo_u32 v194, v193, s8
	v_mul_lo_u32 v196, v196, s8
	v_mul_lo_u32 v198, v195, s8
	v_mul_lo_u32 v200, v199, s8
	v_mul_lo_u32 v202, v197, s8
	v_mul_lo_u32 v206, v203, s8
	v_mul_lo_u32 v208, v201, s8
	v_mul_lo_u32 v210, v209, s8
	v_mul_lo_u32 v212, v207, s8
	v_mul_lo_u32 v214, v213, s8
	v_mul_lo_u32 v216, v211, s8
	v_mul_lo_u32 v218, v217, s8
	v_mul_lo_u32 v220, v215, s8
	v_ashrrev_i32_e32 v191, 31, v190
	v_lshl_add_u64 v[188:189], v[188:189], 2, v[8:9]
	v_ashrrev_i32_e32 v195, 31, v194
	v_ashrrev_i32_e32 v193, 31, v192
	v_ashrrev_i32_e32 v199, 31, v198
	v_ashrrev_i32_e32 v197, 31, v196
	v_ashrrev_i32_e32 v203, 31, v202
	v_ashrrev_i32_e32 v201, 31, v200
	v_ashrrev_i32_e32 v209, 31, v208
	v_ashrrev_i32_e32 v207, 31, v206
	v_ashrrev_i32_e32 v213, 31, v212
	v_ashrrev_i32_e32 v211, 31, v210
	v_ashrrev_i32_e32 v217, 31, v216
	v_ashrrev_i32_e32 v215, 31, v214
	v_ashrrev_i32_e32 v221, 31, v220
	v_ashrrev_i32_e32 v219, 31, v218
	v_lshl_add_u64 v[190:191], v[190:191], 2, v[8:9]
	v_lshl_add_u64 v[192:193], v[192:193], 2, v[8:9]
	v_lshl_add_u64 v[194:195], v[194:195], 2, v[8:9]
	v_lshl_add_u64 v[196:197], v[196:197], 2, v[8:9]
	v_lshl_add_u64 v[198:199], v[198:199], 2, v[8:9]
	v_lshl_add_u64 v[200:201], v[200:201], 2, v[8:9]
	v_lshl_add_u64 v[202:203], v[202:203], 2, v[8:9]
	v_lshl_add_u64 v[206:207], v[206:207], 2, v[8:9]
	v_lshl_add_u64 v[208:209], v[208:209], 2, v[8:9]
	v_lshl_add_u64 v[210:211], v[210:211], 2, v[8:9]
	v_lshl_add_u64 v[212:213], v[212:213], 2, v[8:9]
	v_lshl_add_u64 v[214:215], v[214:215], 2, v[8:9]
	v_lshl_add_u64 v[216:217], v[216:217], 2, v[8:9]
	v_lshl_add_u64 v[218:219], v[218:219], 2, v[8:9]
	v_lshl_add_u64 v[220:221], v[220:221], 2, v[8:9]
	global_load_dword v236, v[188:189], off
	global_load_dword v237, v[190:191], off
	global_load_dword v239, v[192:193], off
	global_load_dword v240, v[194:195], off
	global_load_dword v241, v[196:197], off
	global_load_dword v242, v[198:199], off
	global_load_dword v243, v[200:201], off
	global_load_dword v244, v[202:203], off
	global_load_dword v245, v[206:207], off
	global_load_dword v246, v[208:209], off
	global_load_dword v247, v[210:211], off
	global_load_dword v248, v[212:213], off
	global_load_dword v249, v[214:215], off
	global_load_dword v250, v[216:217], off
	global_load_dword v251, v[218:219], off
	global_load_dword v252, v[220:221], off
	s_waitcnt vmcnt(31)
	ds_write_b32 v18, v66 offset:32768
	s_waitcnt vmcnt(30)
	ds_write_b32 v20, v67 offset:32768
	s_waitcnt vmcnt(29)
	ds_write_b32 v22, v69 offset:32768
	s_waitcnt vmcnt(28)
	ds_write_b32 v24, v70 offset:32768
	s_waitcnt vmcnt(27)
	ds_write_b32 v26, v71 offset:32768
	s_waitcnt vmcnt(26)
	ds_write_b32 v28, v72 offset:32768
	s_waitcnt vmcnt(25)
	ds_write_b32 v30, v73 offset:32768
	s_waitcnt vmcnt(24)
	ds_write_b32 v32, v74 offset:32768
	s_waitcnt vmcnt(23)
	ds_write_b32 v36, v75 offset:32768
	s_waitcnt vmcnt(22)
	ds_write_b32 v38, v76 offset:32768
	s_waitcnt vmcnt(21)
	ds_write_b32 v40, v77 offset:32768
	s_waitcnt vmcnt(20)
	ds_write_b32 v42, v78 offset:32768
	s_waitcnt vmcnt(19)
	ds_write_b32 v44, v79 offset:32768
	s_waitcnt vmcnt(18)
	ds_write_b32 v46, v80 offset:32768
	s_waitcnt vmcnt(17)
	ds_write_b32 v48, v81 offset:32768
	s_waitcnt vmcnt(16)
	ds_write_b32 v50, v82 offset:32768
	s_add_i32 s11, s11, 16
	s_add_i32 s10, s10, 16
	s_add_i32 s12, s12, -16
	v_mad_u64_u32 v[18:19], s[14:15], v204, s7, v[4:5]
	s_cmp_lg_u32 s12, 0
	v_mad_u64_u32 v[20:21], s[14:15], v187, s7, v[4:5]
	v_mad_u64_u32 v[22:23], s[14:15], v223, s7, v[4:5]
	v_mad_u64_u32 v[24:25], s[14:15], v222, s7, v[4:5]
	v_mad_u64_u32 v[26:27], s[14:15], v225, s7, v[4:5]
	v_mad_u64_u32 v[28:29], s[14:15], v224, s7, v[4:5]
	v_mad_u64_u32 v[30:31], s[14:15], v227, s7, v[4:5]
	v_mad_u64_u32 v[32:33], s[14:15], v226, s7, v[4:5]
	v_mad_u64_u32 v[36:37], s[14:15], v229, s7, v[4:5]
	v_mad_u64_u32 v[38:39], s[14:15], v228, s7, v[4:5]
	v_mad_u64_u32 v[40:41], s[14:15], v231, s7, v[4:5]
	v_mad_u64_u32 v[42:43], s[14:15], v230, s7, v[4:5]
	v_mad_u64_u32 v[44:45], s[14:15], v233, s7, v[4:5]
	v_mad_u64_u32 v[46:47], s[14:15], v232, s7, v[4:5]
	v_mad_u64_u32 v[48:49], s[14:15], v235, s7, v[4:5]
	v_mad_u64_u32 v[50:51], s[14:15], v234, s7, v[4:5]
	s_waitcnt vmcnt(15)
; #define GAS __attribute__((address_space(1)))
; #define LAS __attribute__((address_space(3)))
; #define LDS_WAIT() asm volatile("s_waitcnt lgkmcnt(0)" ::: "memory")
; __device__ __forceinline__ unsigned pk2(float lo, float hi) { return pg8::cvt_pk_bf16(lo, hi); }
; template <bool MAP> __device__ __forceinline__ void p0_transpose_item(const float* W, int K, int NS, bf16* WT, LAS float* scr, int item, int nkb, int lane) {
;     ...
;     for (int i = 0; i < 32; ++i) { const int kk = 2 * i + (lane >> 5); scr[kk * 33 + (lane & 31)] = W[(size_t)(k0 + kk) * NS + sc]; }
;     LDS_WAIT(); asm volatile("" ::: "memory");
;     const int c = lane & 7;
; #pragma unroll
;     for (int j = 0; j < 4; ++j) { const int n = (lane >> 3) + 8 * j; const LAS float* s = scr + (8 * c) * 33 + n;
;         v4u o; o.x = pk2(s[0 * 33], s[1 * 33]); o.y = pk2(s[2 * 33], s[3 * 33]); o.z = pk2(s[4 * 33], s[5 * 33]); o.w = pk2(s[6 * 33], s[7 * 33]);
;         *(GAS v4u*)(WT + (size_t)(p0 + n) * K + k0 + 8 * c) = o; }
;     LDS_WAIT(); asm volatile("" ::: "memory");
; template <int LO, int HI> __global__ void __launch_bounds__(NWAVES * 64, 2) fox_fwd(Args args) {
;     ...
;             for (int it = gw; it < 2048; it += NGW) p0_transpose_item<true>(w_in, D, INW, W1T, scr, it, D / 64, lane);
	ds_write_b32 v18, v236 offset:32768
	s_waitcnt vmcnt(14)
	ds_write_b32 v20, v237 offset:32768
	s_waitcnt vmcnt(13)
	ds_write_b32 v22, v239 offset:32768
	s_waitcnt vmcnt(12)
	ds_write_b32 v24, v240 offset:32768
	s_waitcnt vmcnt(11)
	ds_write_b32 v26, v241 offset:32768
	s_waitcnt vmcnt(10)
	ds_write_b32 v28, v242 offset:32768
	s_waitcnt vmcnt(9)
	ds_write_b32 v30, v243 offset:32768
	s_waitcnt vmcnt(8)
	ds_write_b32 v32, v244 offset:32768
	s_waitcnt vmcnt(7)
	ds_write_b32 v36, v245 offset:32768
	s_waitcnt vmcnt(6)
	ds_write_b32 v38, v246 offset:32768
	s_waitcnt vmcnt(5)
	ds_write_b32 v40, v247 offset:32768
	s_waitcnt vmcnt(4)
	ds_write_b32 v42, v248 offset:32768
	s_waitcnt vmcnt(3)
	ds_write_b32 v44, v249 offset:32768
	s_waitcnt vmcnt(2)
	ds_write_b32 v46, v250 offset:32768
	s_waitcnt vmcnt(1)
	ds_write_b32 v48, v251 offset:32768
	s_waitcnt vmcnt(0)
	ds_write_b32 v50, v252 offset:32768
	s_waitcnt lgkmcnt(0)
	v_add_u32_e32 v17, 0x8000, v13
	v_or_b32_e32 v22, s9, v12
	ds_read2_b32 v[8:9], v17 offset1:33
	s_ashr_i32 s5, s4, 31
	v_ashrrev_i32_e32 v23, 31, v22
	s_waitcnt lgkmcnt(0)
	v_cvt_pk_bf16_f32 v18, v8, v9
	ds_read2_b32 v[8:9], v17 offset0:66 offset1:99
	v_lshl_add_u64 v[24:25], s[4:5], 1, v[6:7]
	v_lshlrev_b64 v[22:23], 11, v[22:23]
	s_waitcnt lgkmcnt(0)
	v_cvt_pk_bf16_f32 v19, v8, v9
	ds_read2_b32 v[8:9], v17 offset0:132 offset1:165
	v_lshl_add_u64 v[22:23], v[24:25], 0, v[22:23]
	s_waitcnt lgkmcnt(0)
	v_cvt_pk_bf16_f32 v20, v8, v9
	ds_read2_b32 v[8:9], v17 offset0:198 offset1:231
	s_waitcnt lgkmcnt(0)
	v_cvt_pk_bf16_f32 v21, v8, v9
	global_store_dwordx4 v[22:23], v[18:21], off
	v_or_b32_e32 v22, s9, v14
	ds_read2_b32 v[8:9], v17 offset0:8 offset1:41
	v_ashrrev_i32_e32 v23, 31, v22
	s_waitcnt lgkmcnt(0)
	v_cvt_pk_bf16_f32 v18, v8, v9
	ds_read2_b32 v[8:9], v17 offset0:74 offset1:107
	v_lshlrev_b64 v[22:23], 11, v[22:23]
	s_waitcnt lgkmcnt(0)
	v_cvt_pk_bf16_f32 v19, v8, v9
	ds_read2_b32 v[8:9], v17 offset0:140 offset1:173
	v_lshl_add_u64 v[22:23], v[24:25], 0, v[22:23]
	s_waitcnt lgkmcnt(0)
	v_cvt_pk_bf16_f32 v20, v8, v9
	ds_read2_b32 v[8:9], v17 offset0:206 offset1:239
	s_waitcnt lgkmcnt(0)
	v_cvt_pk_bf16_f32 v21, v8, v9
	global_store_dwordx4 v[22:23], v[18:21], off
	v_or_b32_e32 v22, s9, v15
	ds_read2_b32 v[8:9], v17 offset0:16 offset1:49
	v_ashrrev_i32_e32 v23, 31, v22
	s_waitcnt lgkmcnt(0)
	v_cvt_pk_bf16_f32 v18, v8, v9
	ds_read2_b32 v[8:9], v17 offset0:82 offset1:115
	v_lshlrev_b64 v[22:23], 11, v[22:23]
	s_waitcnt lgkmcnt(0)
	v_cvt_pk_bf16_f32 v19, v8, v9
	ds_read2_b32 v[8:9], v17 offset0:148 offset1:181
	v_lshl_add_u64 v[22:23], v[24:25], 0, v[22:23]
	s_waitcnt lgkmcnt(0)
	v_cvt_pk_bf16_f32 v20, v8, v9
	ds_read2_b32 v[8:9], v17 offset0:214 offset1:247
	s_waitcnt lgkmcnt(0)
	v_cvt_pk_bf16_f32 v21, v8, v9
	global_store_dwordx4 v[22:23], v[18:21], off
	v_or_b32_e32 v22, s9, v16
	ds_read2_b32 v[8:9], v17 offset0:24 offset1:57
	v_ashrrev_i32_e32 v23, 31, v22
	s_waitcnt lgkmcnt(0)
	v_cvt_pk_bf16_f32 v18, v8, v9
	ds_read2_b32 v[8:9], v17 offset0:90 offset1:123
	v_lshlrev_b64 v[22:23], 11, v[22:23]
	s_waitcnt lgkmcnt(0)
	v_cvt_pk_bf16_f32 v19, v8, v9
	ds_read2_b32 v[8:9], v17 offset0:156 offset1:189
	v_lshl_add_u64 v[22:23], v[24:25], 0, v[22:23]
	s_waitcnt lgkmcnt(0)
	v_cvt_pk_bf16_f32 v20, v8, v9
	ds_read2_b32 v[8:9], v17 offset0:222 offset1:255
	s_waitcnt lgkmcnt(0)
	v_cvt_pk_bf16_f32 v21, v8, v9
	global_store_dwordx4 v[22:23], v[18:21], off
	s_waitcnt lgkmcnt(0)
	s_add_i32 s33, s33, s6
	s_cmpk_gt_i32 s33, 0x7ff
	s_cbranch_scc0 .LBB0_136
